# cmp1 in-loop A loader: pos loaded once, four src loads in flight before conversion
# speedup vs baseline: 1.0598x; 1.0062x over previous
.LBB0_435:
	s_add_i32 s9, s8, 2
	s_min_u32 s16, s9, 31
	s_waitcnt vmcnt(4)
	v_lshl_or_b32 v126, s16, 6, v158
	v_lshlrev_b32_e32 v127, 2, v126
	v_mov_b32_e32 v169, 0
	global_load_dwordx4 v[236:239], v127, s[40:41] offset:16
	global_load_dwordx4 v[232:235], v127, s[40:41]
	v_mov_b32_e32 v94, 0
	v_mov_b32_e32 v95, 0
	v_mov_b32_e32 v96, 0
	v_mov_b32_e32 v97, 0
	s_and_saveexec_b64 s[4:5], s[52:53]
	v_lshl_add_u32 v0, s16, 7, v160
	v_lshl_add_u64 v[94:95], v[176:177], 0, v[0:1]
	global_load_dwordx4 v[94:97], v[94:95], off
	s_or_b64 exec, exec, s[4:5]
	v_mov_b32_e32 v106, 0
	v_mov_b32_e32 v107, 0
	v_mov_b32_e32 v108, 0
	v_mov_b32_e32 v109, 0
	s_and_saveexec_b64 s[4:5], s[56:57]
	v_lshl_add_u32 v0, s16, 7, v164
	v_lshl_add_u64 v[104:105], v[178:179], 0, v[0:1]
	global_load_dwordx4 v[106:109], v[104:105], off
	s_or_b64 exec, exec, s[4:5]
	v_mov_b32_e32 v102, 0
	v_mov_b32_e32 v103, 0
	v_mov_b32_e32 v104, 0
	v_mov_b32_e32 v105, 0
	s_and_saveexec_b64 s[4:5], s[58:59]
	v_lshl_add_u32 v0, s16, 7, v168
	v_lshl_add_u64 v[102:103], v[180:181], 0, v[0:1]
	global_load_dwordx4 v[102:105], v[102:103], off
	s_or_b64 exec, exec, s[4:5]
	v_mov_b32_e32 v122, 0
	v_mov_b32_e32 v123, 0
	v_mov_b32_e32 v124, 0
	v_mov_b32_e32 v125, 0
	s_and_saveexec_b64 s[4:5], s[60:61]
	v_lshl_add_u32 v0, s16, 7, v172
	v_lshl_add_u64 v[122:123], v[182:183], 0, v[0:1]
	global_load_dwordx4 v[122:125], v[122:123], off
	s_or_b64 exec, exec, s[4:5]
	v_or_b32_e32 v0, v126, v162
	v_lshl_add_u64 v[98:99], v[0:1], 1, s[54:55]
	global_load_dwordx4 v[98:101], v[98:99], off
	v_or_b32_e32 v0, v126, v166
	v_lshl_add_u64 v[114:115], v[0:1], 1, s[54:55]
	global_load_dwordx4 v[114:117], v[114:115], off
	v_or_b32_e32 v0, v126, v170
	v_lshl_add_u64 v[118:119], v[0:1], 1, s[54:55]
	global_load_dwordx4 v[118:121], v[118:119], off
	s_and_saveexec_b64 s[4:5], s[52:53]
	s_waitcnt vmcnt(6)
	v_lshlrev_b32_e32 v240, 16, v94
	v_and_b32_e32 v241, 0xffff0000, v94
	v_pk_add_f32 v[240:241], v[232:233], v[240:241]
	s_nop 0
	v_cvt_pk_bf16_f32 v94, v240, v241
	v_lshlrev_b32_e32 v242, 16, v95
	v_and_b32_e32 v243, 0xffff0000, v95
	v_pk_add_f32 v[242:243], v[234:235], v[242:243]
	s_nop 0
	v_cvt_pk_bf16_f32 v95, v242, v243
	v_lshlrev_b32_e32 v240, 16, v96
	v_and_b32_e32 v241, 0xffff0000, v96
	v_pk_add_f32 v[240:241], v[236:237], v[240:241]
	s_nop 0
	v_cvt_pk_bf16_f32 v96, v240, v241
	v_lshlrev_b32_e32 v242, 16, v97
	v_and_b32_e32 v243, 0xffff0000, v97
	v_pk_add_f32 v[242:243], v[238:239], v[242:243]
	s_nop 0
	v_cvt_pk_bf16_f32 v97, v242, v243
	s_or_b64 exec, exec, s[4:5]
	s_and_saveexec_b64 s[4:5], s[56:57]
	s_waitcnt vmcnt(5)
	v_lshlrev_b32_e32 v240, 16, v106
	v_and_b32_e32 v241, 0xffff0000, v106
	v_pk_add_f32 v[240:241], v[232:233], v[240:241]
	s_nop 0
	v_cvt_pk_bf16_f32 v106, v240, v241
	v_lshlrev_b32_e32 v242, 16, v107
	v_and_b32_e32 v243, 0xffff0000, v107
	v_pk_add_f32 v[242:243], v[234:235], v[242:243]
	s_nop 0
	v_cvt_pk_bf16_f32 v107, v242, v243
	v_lshlrev_b32_e32 v240, 16, v108
	v_and_b32_e32 v241, 0xffff0000, v108
	v_pk_add_f32 v[240:241], v[236:237], v[240:241]
	s_nop 0
	v_cvt_pk_bf16_f32 v108, v240, v241
	v_lshlrev_b32_e32 v242, 16, v109
	v_and_b32_e32 v243, 0xffff0000, v109
	v_pk_add_f32 v[242:243], v[238:239], v[242:243]
	s_nop 0
	v_cvt_pk_bf16_f32 v109, v242, v243
	s_or_b64 exec, exec, s[4:5]
	s_and_saveexec_b64 s[4:5], s[58:59]
	s_waitcnt vmcnt(4)
	v_lshlrev_b32_e32 v240, 16, v102
	v_and_b32_e32 v241, 0xffff0000, v102
	v_pk_add_f32 v[240:241], v[232:233], v[240:241]
	s_nop 0
	v_cvt_pk_bf16_f32 v102, v240, v241
	v_lshlrev_b32_e32 v242, 16, v103
	v_and_b32_e32 v243, 0xffff0000, v103
	v_pk_add_f32 v[242:243], v[234:235], v[242:243]
	s_nop 0
	v_cvt_pk_bf16_f32 v103, v242, v243
	v_lshlrev_b32_e32 v240, 16, v104
	v_and_b32_e32 v241, 0xffff0000, v104
	v_pk_add_f32 v[240:241], v[236:237], v[240:241]
	s_nop 0
	v_cvt_pk_bf16_f32 v104, v240, v241
	v_lshlrev_b32_e32 v242, 16, v105
	v_and_b32_e32 v243, 0xffff0000, v105
	v_pk_add_f32 v[242:243], v[238:239], v[242:243]
	s_nop 0
	v_cvt_pk_bf16_f32 v105, v242, v243
	s_or_b64 exec, exec, s[4:5]
	s_and_saveexec_b64 s[4:5], s[60:61]
	s_waitcnt vmcnt(3)
	v_lshlrev_b32_e32 v240, 16, v122
	v_and_b32_e32 v241, 0xffff0000, v122
	v_pk_add_f32 v[240:241], v[232:233], v[240:241]
	s_nop 0
	v_cvt_pk_bf16_f32 v122, v240, v241
	v_lshlrev_b32_e32 v242, 16, v123
	v_and_b32_e32 v243, 0xffff0000, v123
	v_pk_add_f32 v[242:243], v[234:235], v[242:243]
	s_nop 0
	v_cvt_pk_bf16_f32 v123, v242, v243
	v_lshlrev_b32_e32 v240, 16, v124
	v_and_b32_e32 v241, 0xffff0000, v124
	v_pk_add_f32 v[240:241], v[236:237], v[240:241]
	s_nop 0
	v_cvt_pk_bf16_f32 v124, v240, v241
	v_lshlrev_b32_e32 v242, 16, v125
	v_and_b32_e32 v243, 0xffff0000, v125
	v_pk_add_f32 v[242:243], v[238:239], v[242:243]
	s_nop 0
	v_cvt_pk_bf16_f32 v125, v242, v243
	s_or_b64 exec, exec, s[4:5]
	ds_read_b128 v[214:217], v159
	ds_read_b128 v[218:221], v161 offset:18432
	ds_read_b128 v[222:225], v159 offset:4608
	v_or_b32_e32 v0, v126, v174
	v_lshl_add_u64 v[126:127], v[0:1], 1, s[54:55]
	s_min_u32 s16, s8, 28
	s_waitcnt lgkmcnt(1)
	v_mfma_f32_32x32x16_bf16 v[50:65], v[214:217], v[218:221], v[50:65]
	s_add_i32 s16, s16, 3
	s_waitcnt lgkmcnt(0)
	v_mfma_f32_32x32x16_bf16 v[18:33], v[222:225], v[218:221], v[18:33]
	ds_read_b128 v[218:221], v161 offset:23040
	s_waitcnt lgkmcnt(0)
	v_mfma_f32_32x32x16_bf16 v[34:49], v[214:217], v[218:221], v[34:49]
	v_mfma_f32_32x32x16_bf16 v[2:17], v[222:225], v[218:221], v[2:17]
	ds_read_b128 v[214:217], v159 offset:32
	ds_read_b128 v[218:221], v161 offset:18464
	ds_read_b128 v[222:225], v163 offset:4608
	s_waitcnt lgkmcnt(1)
	v_mfma_f32_32x32x16_bf16 v[50:65], v[214:217], v[218:221], v[50:65]
	s_waitcnt lgkmcnt(0)
	v_mfma_f32_32x32x16_bf16 v[18:33], v[222:225], v[218:221], v[18:33]
	ds_read_b128 v[218:221], v161 offset:23072
	s_waitcnt lgkmcnt(0)
	v_mfma_f32_32x32x16_bf16 v[34:49], v[214:217], v[218:221], v[34:49]
	v_mfma_f32_32x32x16_bf16 v[2:17], v[222:225], v[218:221], v[2:17]
	ds_read_b128 v[214:217], v159 offset:64
	ds_read_b128 v[218:221], v161 offset:18496
	global_load_dwordx4 v[126:129], v[126:127], off
	ds_read_b128 v[222:225], v165 offset:4608
	s_waitcnt lgkmcnt(1)
	v_mfma_f32_32x32x16_bf16 v[50:65], v[214:217], v[218:221], v[50:65]
	s_waitcnt lgkmcnt(0)
	v_mfma_f32_32x32x16_bf16 v[18:33], v[222:225], v[218:221], v[18:33]
	ds_read_b128 v[218:221], v161 offset:23104
	s_waitcnt lgkmcnt(0)
	v_mfma_f32_32x32x16_bf16 v[34:49], v[214:217], v[218:221], v[34:49]
	v_mfma_f32_32x32x16_bf16 v[2:17], v[222:225], v[218:221], v[2:17]
	ds_read_b128 v[214:217], v159 offset:96
	ds_read_b128 v[218:221], v161 offset:18528
	ds_read_b128 v[222:225], v167 offset:4608
	ds_read_b128 v[226:229], v161 offset:23136
	ds_write_b128 v131, v[66:69] offset:36864
	s_waitcnt vmcnt(7)
	ds_write_b128 v131, v[70:73] offset:55296
	ds_write_b128 v135, v[78:81] offset:36864
	v_lshl_or_b32 v66, s16, 6, v158
	s_waitcnt vmcnt(6)
	ds_write_b128 v135, v[82:85] offset:55296
	ds_write_b128 v152, v[74:77] offset:36864
	s_waitcnt vmcnt(5)
	ds_write_b128 v152, v[86:89] offset:55296
	ds_write_b128 v156, v[90:93] offset:36864
	s_waitcnt vmcnt(4)
	ds_write_b128 v156, v[110:113] offset:55296
	v_lshlrev_b32_e32 v110, 2, v66
	v_mov_b32_e32 v67, 0
	s_waitcnt lgkmcnt(10)
	v_mfma_f32_32x32x16_bf16 v[50:65], v[214:217], v[218:221], v[50:65]
	v_mov_b32_e32 v68, 0
	v_mov_b32_e32 v69, 0
	s_waitcnt lgkmcnt(0)
	s_barrier
	v_mfma_f32_32x32x16_bf16 v[18:33], v[222:225], v[218:221], v[18:33]
	v_mfma_f32_32x32x16_bf16 v[34:49], v[214:217], v[226:229], v[34:49]
	v_mfma_f32_32x32x16_bf16 v[2:17], v[222:225], v[226:229], v[2:17]
	global_load_dwordx4 v[236:239], v110, s[40:41] offset:16
	global_load_dwordx4 v[232:235], v110, s[40:41]
	s_and_saveexec_b64 s[4:5], s[52:53]
	v_lshl_add_u32 v0, s16, 7, v160
	v_lshl_add_u64 v[244:245], v[176:177], 0, v[0:1]
	global_load_dwordx4 v[244:247], v[244:245], off
	s_or_b64 exec, exec, s[4:5]
	v_mov_b32_e32 v78, 0
	v_mov_b32_e32 v79, 0
	v_mov_b32_e32 v80, 0
	v_mov_b32_e32 v81, 0
	s_and_saveexec_b64 s[4:5], s[56:57]
	v_lshl_add_u32 v0, s16, 7, v164
	v_lshl_add_u64 v[76:77], v[178:179], 0, v[0:1]
	global_load_dwordx4 v[78:81], v[76:77], off
	s_or_b64 exec, exec, s[4:5]
	v_mov_b32_e32 v74, 0
	v_mov_b32_e32 v75, 0
	v_mov_b32_e32 v76, 0
	v_mov_b32_e32 v77, 0
	s_and_saveexec_b64 s[4:5], s[58:59]
	v_lshl_add_u32 v0, s16, 7, v168
	v_lshl_add_u64 v[74:75], v[180:181], 0, v[0:1]
	global_load_dwordx4 v[74:77], v[74:75], off
	s_or_b64 exec, exec, s[4:5]
	v_mov_b32_e32 v90, 0
	v_mov_b32_e32 v91, 0
	v_mov_b32_e32 v92, 0
	v_mov_b32_e32 v93, 0
	s_and_saveexec_b64 s[4:5], s[60:61]
	v_lshl_add_u32 v0, s16, 7, v172
	v_lshl_add_u64 v[90:91], v[182:183], 0, v[0:1]
	global_load_dwordx4 v[90:93], v[90:91], off
	s_or_b64 exec, exec, s[4:5]
	v_add_u32_e32 v0, v66, v162
	v_lshl_add_u64 v[70:71], v[0:1], 1, s[54:55]
	global_load_dwordx4 v[70:73], v[70:71], off
	v_add_u32_e32 v0, v66, v166
	v_lshl_add_u64 v[82:83], v[0:1], 1, s[54:55]
	global_load_dwordx4 v[82:85], v[82:83], off
	v_add_u32_e32 v0, v66, v170
	v_lshl_add_u64 v[86:87], v[0:1], 1, s[54:55]
	global_load_dwordx4 v[86:89], v[86:87], off
	s_and_saveexec_b64 s[4:5], s[52:53]
	s_waitcnt vmcnt(6)
	v_lshlrev_b32_e32 v240, 16, v244
	v_and_b32_e32 v241, 0xffff0000, v244
	v_pk_add_f32 v[240:241], v[232:233], v[240:241]
	s_nop 0
	v_cvt_pk_bf16_f32 v169, v240, v241
	v_lshlrev_b32_e32 v242, 16, v245
	v_and_b32_e32 v243, 0xffff0000, v245
	v_pk_add_f32 v[242:243], v[234:235], v[242:243]
	s_nop 0
	v_cvt_pk_bf16_f32 v67, v242, v243
	v_lshlrev_b32_e32 v240, 16, v246
	v_and_b32_e32 v241, 0xffff0000, v246
	v_pk_add_f32 v[240:241], v[236:237], v[240:241]
	s_nop 0
	v_cvt_pk_bf16_f32 v68, v240, v241
	v_lshlrev_b32_e32 v242, 16, v247
	v_and_b32_e32 v243, 0xffff0000, v247
	v_pk_add_f32 v[242:243], v[238:239], v[242:243]
	s_nop 0
	v_cvt_pk_bf16_f32 v69, v242, v243
	s_or_b64 exec, exec, s[4:5]
	s_and_saveexec_b64 s[4:5], s[56:57]
	s_waitcnt vmcnt(5)
	v_lshlrev_b32_e32 v240, 16, v78
	v_and_b32_e32 v241, 0xffff0000, v78
	v_pk_add_f32 v[240:241], v[232:233], v[240:241]
	s_nop 0
	v_cvt_pk_bf16_f32 v78, v240, v241
	v_lshlrev_b32_e32 v242, 16, v79
	v_and_b32_e32 v243, 0xffff0000, v79
	v_pk_add_f32 v[242:243], v[234:235], v[242:243]
	s_nop 0
	v_cvt_pk_bf16_f32 v79, v242, v243
	v_lshlrev_b32_e32 v240, 16, v80
	v_and_b32_e32 v241, 0xffff0000, v80
	v_pk_add_f32 v[240:241], v[236:237], v[240:241]
	s_nop 0
	v_cvt_pk_bf16_f32 v80, v240, v241
	v_lshlrev_b32_e32 v242, 16, v81
	v_and_b32_e32 v243, 0xffff0000, v81
	v_pk_add_f32 v[242:243], v[238:239], v[242:243]
	s_nop 0
	v_cvt_pk_bf16_f32 v81, v242, v243
	s_or_b64 exec, exec, s[4:5]
	s_and_saveexec_b64 s[4:5], s[58:59]
	s_waitcnt vmcnt(4)
	v_lshlrev_b32_e32 v240, 16, v74
	v_and_b32_e32 v241, 0xffff0000, v74
	v_pk_add_f32 v[240:241], v[232:233], v[240:241]
	s_nop 0
	v_cvt_pk_bf16_f32 v74, v240, v241
	v_lshlrev_b32_e32 v242, 16, v75
	v_and_b32_e32 v243, 0xffff0000, v75
	v_pk_add_f32 v[242:243], v[234:235], v[242:243]
	s_nop 0
	v_cvt_pk_bf16_f32 v75, v242, v243
	v_lshlrev_b32_e32 v240, 16, v76
	v_and_b32_e32 v241, 0xffff0000, v76
	v_pk_add_f32 v[240:241], v[236:237], v[240:241]
	s_nop 0
	v_cvt_pk_bf16_f32 v76, v240, v241
	v_lshlrev_b32_e32 v242, 16, v77
	v_and_b32_e32 v243, 0xffff0000, v77
	v_pk_add_f32 v[242:243], v[238:239], v[242:243]
	s_nop 0
	v_cvt_pk_bf16_f32 v77, v242, v243
	s_or_b64 exec, exec, s[4:5]
	s_and_saveexec_b64 s[4:5], s[60:61]
	s_waitcnt vmcnt(3)
	v_lshlrev_b32_e32 v240, 16, v90
	v_and_b32_e32 v241, 0xffff0000, v90
	v_pk_add_f32 v[240:241], v[232:233], v[240:241]
	s_nop 0
	v_cvt_pk_bf16_f32 v90, v240, v241
	v_lshlrev_b32_e32 v242, 16, v91
	v_and_b32_e32 v243, 0xffff0000, v91
	v_pk_add_f32 v[242:243], v[234:235], v[242:243]
	s_nop 0
	v_cvt_pk_bf16_f32 v91, v242, v243
	v_lshlrev_b32_e32 v240, 16, v92
	v_and_b32_e32 v241, 0xffff0000, v92
	v_pk_add_f32 v[240:241], v[236:237], v[240:241]
	s_nop 0
	v_cvt_pk_bf16_f32 v92, v240, v241
	v_lshlrev_b32_e32 v242, 16, v93
	v_and_b32_e32 v243, 0xffff0000, v93
	v_pk_add_f32 v[242:243], v[238:239], v[242:243]
	s_nop 0
	v_cvt_pk_bf16_f32 v93, v242, v243
	s_or_b64 exec, exec, s[4:5]
	ds_read_b128 v[110:113], v159 offset:36864
	ds_read_b128 v[214:217], v161 offset:55296
	ds_read_b128 v[218:221], v159 offset:41472
	v_add_u32_e32 v0, v66, v174
	v_lshl_add_u64 v[222:223], v[0:1], 1, s[54:55]
	s_cmp_gt_u32 s8, 29
	s_waitcnt lgkmcnt(1)
	v_mfma_f32_32x32x16_bf16 v[50:65], v[110:113], v[214:217], v[50:65]
	s_cselect_b64 s[4:5], -1, 0
	s_and_b64 vcc, exec, s[4:5]
	s_waitcnt lgkmcnt(0)
	v_mfma_f32_32x32x16_bf16 v[18:33], v[218:221], v[214:217], v[18:33]
	ds_read_b128 v[214:217], v161 offset:59904
	s_waitcnt lgkmcnt(0)
	v_mfma_f32_32x32x16_bf16 v[34:49], v[110:113], v[214:217], v[34:49]
	v_mfma_f32_32x32x16_bf16 v[2:17], v[218:221], v[214:217], v[2:17]
	ds_read_b128 v[110:113], v159 offset:36896
	ds_read_b128 v[214:217], v161 offset:55328
	ds_read_b128 v[218:221], v163 offset:41472
	s_waitcnt lgkmcnt(1)
	v_mfma_f32_32x32x16_bf16 v[50:65], v[110:113], v[214:217], v[50:65]
	s_waitcnt lgkmcnt(0)
	v_mfma_f32_32x32x16_bf16 v[18:33], v[218:221], v[214:217], v[18:33]
	ds_read_b128 v[214:217], v161 offset:59936
	s_waitcnt lgkmcnt(0)
	v_mfma_f32_32x32x16_bf16 v[34:49], v[110:113], v[214:217], v[34:49]
	v_mfma_f32_32x32x16_bf16 v[2:17], v[218:221], v[214:217], v[2:17]
	ds_read_b128 v[110:113], v159 offset:36928
	ds_read_b128 v[214:217], v161 offset:55360
	ds_read_b128 v[218:221], v165 offset:41472
	s_waitcnt lgkmcnt(1)
	v_mfma_f32_32x32x16_bf16 v[50:65], v[110:113], v[214:217], v[50:65]
	s_waitcnt lgkmcnt(0)
	v_mfma_f32_32x32x16_bf16 v[18:33], v[218:221], v[214:217], v[18:33]
	ds_read_b128 v[214:217], v161 offset:59968
	s_waitcnt lgkmcnt(0)
	v_mfma_f32_32x32x16_bf16 v[34:49], v[110:113], v[214:217], v[34:49]
	v_mfma_f32_32x32x16_bf16 v[2:17], v[218:221], v[214:217], v[2:17]
	ds_read_b128 v[110:113], v159 offset:36960
	ds_read_b128 v[214:217], v161 offset:55392
	ds_read_b128 v[218:221], v167 offset:41472
	s_waitcnt lgkmcnt(1)
	v_mfma_f32_32x32x16_bf16 v[50:65], v[110:113], v[214:217], v[50:65]
	s_waitcnt lgkmcnt(0)
	v_mfma_f32_32x32x16_bf16 v[18:33], v[218:221], v[214:217], v[18:33]
	ds_read_b128 v[214:217], v161 offset:60000
	s_waitcnt lgkmcnt(0)
	v_mfma_f32_32x32x16_bf16 v[34:49], v[110:113], v[214:217], v[34:49]
	global_load_dwordx4 v[110:113], v[222:223], off
	v_mfma_f32_32x32x16_bf16 v[2:17], v[218:221], v[214:217], v[2:17]
	s_cbranch_vccnz .LBB0_434
	ds_write_b128 v131, v[94:97]
	s_waitcnt vmcnt(7)
	ds_write_b128 v131, v[98:101] offset:18432
	ds_write_b128 v135, v[106:109]
	s_waitcnt vmcnt(6)
	ds_write_b128 v135, v[114:117] offset:18432
	ds_write_b128 v152, v[102:105]
	s_waitcnt vmcnt(5)
	ds_write_b128 v152, v[118:121] offset:18432
	ds_write_b128 v156, v[122:125]
	s_waitcnt vmcnt(4)
	ds_write_b128 v156, v[126:129] offset:18432
	s_branch .LBB0_434
